# fused epilogues: tagged partial-sum exchange (8-byte value+phase tag slots polled by the row threads; arrival counter, ordering wait, single-wave poll and one barrier removed)
# baseline (speedup 1.0000x reference)
.LBB0_362:
	v_mov_b32_e32 v12, v216
	s_cmpk_lg_i32 s74, 0x100
	s_waitcnt vmcnt(0)
	s_barrier
	s_cselect_b64 s[0:1], -1, 0
	v_readfirstlane_b32 s23, v12
	s_ashr_i32 s33, s23, 8
	s_bfe_u32 s38, s23, 0x20006
	s_cmp_eq_u32 s93, 44
	s_cselect_b64 s[4:5], -1, 0
	s_cmp_lg_u32 s93, 44
	s_cselect_b64 s[8:9], -1, 0
	s_or_b64 s[0:1], s[0:1], s[8:9]
	s_cmp_gt_i32 s22, 63
	s_cselect_b64 s[8:9], -1, 0
	v_readlane_b32 s78, v254, 8
	s_or_b64 s[0:1], s[0:1], s[8:9]
	v_readlane_b32 s76, v254, 6
	v_readlane_b32 s79, v254, 9
	v_readlane_b32 s80, v254, 21
	v_readlane_b32 s92, v254, 23
	v_and_b32_e32 v184, 15, v12
	v_bfe_u32 v185, v12, 4, 2
	s_andn2_b64 vcc, exec, s[0:1]
	s_mov_b64 s[0:1], -1
	v_readlane_b32 s77, v254, 7
	v_readlane_b32 s75, v254, 10
	v_readlane_b32 s81, v254, 22
	s_movk_i32 s79, 0x5000
	s_mov_b32 s82, 0x1400000
	s_mov_b32 s83, 0x1800000
	s_mov_b32 s84, 0x1c00000
	s_mov_b32 s85, 0xf800000
	s_movk_i32 s86, 0x1000
	s_movk_i32 s87, 0x48
	s_movk_i32 s88, 0x1600
	s_mov_b64 s[90:91], 0x1000
	v_readlane_b32 s93, v254, 24
	s_cbranch_vccz .LBB0_401
	s_waitcnt vmcnt(0)
	v_lshl_or_b32 v14, s33, 6, v184
	s_lshl_b32 s100, s20, 8
	s_lshl_b32 s101, s38, 5
	s_or_b32 s100, s100, s101
	v_lshl_or_b32 v225, v185, 2, s100
	v_lshlrev_b32_e32 v222, 2, v225
	s_lshl_b32 s100, s22, 8
	v_add_u32_e32 v12, s100, v14
	v_lshl_add_u32 v12, v12, 10, v225
	v_lshlrev_b32_e32 v220, 2, v12
	v_mov_b32_e32 v224, v220
	v_lshlrev_b32_e32 v221, 2, v14
	s_lshl_b32 s100, s38, 4
	v_lshl_add_u32 v223, v14, 6, s100
	v_lshl_add_u32 v223, v185, 2, v223
	s_lshr_b32 s100, s22, 3
	s_mul_i32 s100, s100, 0x9000
	s_add_u32 s100, s45, s100
	s_addc_u32 s101, s68, 0
	global_load_dwordx4 v[140:143], v222, s[100:101]
	global_load_dwordx4 v[144:147], v222, s[100:101] offset:64
	global_load_dwordx4 v[148:151], v222, s[100:101] offset:512
	global_load_dwordx4 v[152:155], v222, s[100:101] offset:576
	global_load_dwordx4 v[156:159], v224, s[12:13]
	global_load_dwordx4 v[160:163], v224, s[12:13] offset:64
	global_load_dwordx4 v[164:167], v224, s[12:13] offset:512
	global_load_dwordx4 v[168:171], v224, s[12:13] offset:576
	v_add_u32_e32 v224, 0x10000, v224
	global_load_dwordx4 v[172:175], v224, s[12:13]
	global_load_dwordx4 v[176:179], v224, s[12:13] offset:64
	global_load_dwordx4 v[180:183], v224, s[12:13] offset:512
	global_load_dwordx4 v[184:187], v224, s[12:13] offset:576
	v_add_u32_e32 v224, 0x10000, v224
	global_load_dwordx4 v[188:191], v224, s[12:13]
	global_load_dwordx4 v[192:195], v224, s[12:13] offset:64
	global_load_dwordx4 v[196:199], v224, s[12:13] offset:512
	global_load_dwordx4 v[200:203], v224, s[12:13] offset:576
	v_add_u32_e32 v224, 0x10000, v224
	global_load_dwordx4 v[204:207], v224, s[12:13]
	global_load_dwordx4 v[208:211], v224, s[12:13] offset:64
	global_load_dwordx4 v[212:215], v224, s[12:13] offset:512
	global_load_dwordx4 v[228:231], v224, s[12:13] offset:576
	v_add_u32_e32 v224, 0x50000, v224
	s_waitcnt vmcnt(12)
	v_pk_mul_f32 v[140:141], v[140:141], 0.5 op_sel_hi:[1,0]
	v_pk_mul_f32 v[142:143], v[142:143], 0.5 op_sel_hi:[1,0]
	v_pk_mul_f32 v[144:145], v[144:145], 0.5 op_sel_hi:[1,0]
	v_pk_mul_f32 v[146:147], v[146:147], 0.5 op_sel_hi:[1,0]
	v_pk_mul_f32 v[148:149], v[148:149], 0.5 op_sel_hi:[1,0]
	v_pk_mul_f32 v[150:151], v[150:151], 0.5 op_sel_hi:[1,0]
	v_pk_mul_f32 v[152:153], v[152:153], 0.5 op_sel_hi:[1,0]
	v_pk_mul_f32 v[154:155], v[154:155], 0.5 op_sel_hi:[1,0]
	v_pk_fma_f32 v[128:129], v[128:129], v[140:141], v[156:157]
	v_pk_fma_f32 v[130:131], v[130:131], v[142:143], v[158:159]
	v_pk_fma_f32 v[124:125], v[124:125], v[144:145], v[160:161]
	v_pk_fma_f32 v[126:127], v[126:127], v[146:147], v[162:163]
	v_pk_fma_f32 v[120:121], v[120:121], v[148:149], v[164:165]
	v_pk_fma_f32 v[122:123], v[122:123], v[150:151], v[166:167]
	v_pk_fma_f32 v[116:117], v[116:117], v[152:153], v[168:169]
	v_pk_fma_f32 v[118:119], v[118:119], v[154:155], v[170:171]
	global_load_dwordx4 v[156:159], v224, s[12:13]
	global_load_dwordx4 v[160:163], v224, s[12:13] offset:64
	global_load_dwordx4 v[164:167], v224, s[12:13] offset:512
	global_load_dwordx4 v[168:171], v224, s[12:13] offset:576
	v_add_u32_e32 v224, 0x10000, v224
	v_mul_f32_e32 v132, v129, v129
	v_mul_f32_e32 v133, v131, v131
	v_fmac_f32_e32 v132, v128, v128
	v_fmac_f32_e32 v133, v130, v130
	v_add_f32_e32 v134, v132, v133
	v_mul_f32_e32 v132, v125, v125
	v_mul_f32_e32 v133, v127, v127
	v_fmac_f32_e32 v132, v124, v124
	v_fmac_f32_e32 v133, v126, v126
	v_add_f32_e32 v132, v132, v133
	v_add_f32_e32 v134, v134, v132
	v_mul_f32_e32 v132, v121, v121
	v_mul_f32_e32 v133, v123, v123
	v_fmac_f32_e32 v132, v120, v120
	v_fmac_f32_e32 v133, v122, v122
	v_add_f32_e32 v132, v132, v133
	v_add_f32_e32 v134, v134, v132
	v_mul_f32_e32 v132, v117, v117
	v_mul_f32_e32 v133, v119, v119
	v_fmac_f32_e32 v132, v116, v116
	v_fmac_f32_e32 v133, v118, v118
	v_add_f32_e32 v132, v132, v133
	v_add_f32_e32 v134, v134, v132
	ds_write_b32 v223, v134
	s_waitcnt vmcnt(12)
	v_pk_fma_f32 v[112:113], v[112:113], v[140:141], v[172:173]
	v_pk_fma_f32 v[114:115], v[114:115], v[142:143], v[174:175]
	v_pk_fma_f32 v[108:109], v[108:109], v[144:145], v[176:177]
	v_pk_fma_f32 v[110:111], v[110:111], v[146:147], v[178:179]
	v_pk_fma_f32 v[104:105], v[104:105], v[148:149], v[180:181]
	v_pk_fma_f32 v[106:107], v[106:107], v[150:151], v[182:183]
	v_pk_fma_f32 v[100:101], v[100:101], v[152:153], v[184:185]
	v_pk_fma_f32 v[102:103], v[102:103], v[154:155], v[186:187]
	global_load_dwordx4 v[172:175], v224, s[12:13]
	global_load_dwordx4 v[176:179], v224, s[12:13] offset:64
	global_load_dwordx4 v[180:183], v224, s[12:13] offset:512
	global_load_dwordx4 v[184:187], v224, s[12:13] offset:576
	v_add_u32_e32 v224, 0x10000, v224
	v_mul_f32_e32 v132, v113, v113
	v_mul_f32_e32 v133, v115, v115
	v_fmac_f32_e32 v132, v112, v112
	v_fmac_f32_e32 v133, v114, v114
	v_add_f32_e32 v135, v132, v133
	v_mul_f32_e32 v132, v109, v109
	v_mul_f32_e32 v133, v111, v111
	v_fmac_f32_e32 v132, v108, v108
	v_fmac_f32_e32 v133, v110, v110
	v_add_f32_e32 v132, v132, v133
	v_add_f32_e32 v135, v135, v132
	v_mul_f32_e32 v132, v105, v105
	v_mul_f32_e32 v133, v107, v107
	v_fmac_f32_e32 v132, v104, v104
	v_fmac_f32_e32 v133, v106, v106
	v_add_f32_e32 v132, v132, v133
	v_add_f32_e32 v135, v135, v132
	v_mul_f32_e32 v132, v101, v101
	v_mul_f32_e32 v133, v103, v103
	v_fmac_f32_e32 v132, v100, v100
	v_fmac_f32_e32 v133, v102, v102
	v_add_f32_e32 v132, v132, v133
	v_add_f32_e32 v135, v135, v132
	ds_write_b32 v223, v135 offset:1024
	s_waitcnt vmcnt(12)
	v_pk_fma_f32 v[96:97], v[96:97], v[140:141], v[188:189]
	v_pk_fma_f32 v[98:99], v[98:99], v[142:143], v[190:191]
	v_pk_fma_f32 v[92:93], v[92:93], v[144:145], v[192:193]
	v_pk_fma_f32 v[94:95], v[94:95], v[146:147], v[194:195]
	v_pk_fma_f32 v[88:89], v[88:89], v[148:149], v[196:197]
	v_pk_fma_f32 v[90:91], v[90:91], v[150:151], v[198:199]
	v_pk_fma_f32 v[84:85], v[84:85], v[152:153], v[200:201]
	v_pk_fma_f32 v[86:87], v[86:87], v[154:155], v[202:203]
	global_load_dwordx4 v[188:191], v224, s[12:13]
	global_load_dwordx4 v[192:195], v224, s[12:13] offset:64
	global_load_dwordx4 v[196:199], v224, s[12:13] offset:512
	global_load_dwordx4 v[200:203], v224, s[12:13] offset:576
	v_add_u32_e32 v224, 0x10000, v224
	v_mul_f32_e32 v132, v97, v97
	v_mul_f32_e32 v133, v99, v99
	v_fmac_f32_e32 v132, v96, v96
	v_fmac_f32_e32 v133, v98, v98
	v_add_f32_e32 v134, v132, v133
	v_mul_f32_e32 v132, v93, v93
	v_mul_f32_e32 v133, v95, v95
	v_fmac_f32_e32 v132, v92, v92
	v_fmac_f32_e32 v133, v94, v94
	v_add_f32_e32 v132, v132, v133
	v_add_f32_e32 v134, v134, v132
	v_mul_f32_e32 v132, v89, v89
	v_mul_f32_e32 v133, v91, v91
	v_fmac_f32_e32 v132, v88, v88
	v_fmac_f32_e32 v133, v90, v90
	v_add_f32_e32 v132, v132, v133
	v_add_f32_e32 v134, v134, v132
	v_mul_f32_e32 v132, v85, v85
	v_mul_f32_e32 v133, v87, v87
	v_fmac_f32_e32 v132, v84, v84
	v_fmac_f32_e32 v133, v86, v86
	v_add_f32_e32 v132, v132, v133
	v_add_f32_e32 v134, v134, v132
	ds_write_b32 v223, v134 offset:2048
	s_waitcnt vmcnt(12)
	v_pk_fma_f32 v[80:81], v[80:81], v[140:141], v[204:205]
	v_pk_fma_f32 v[82:83], v[82:83], v[142:143], v[206:207]
	v_pk_fma_f32 v[76:77], v[76:77], v[144:145], v[208:209]
	v_pk_fma_f32 v[78:79], v[78:79], v[146:147], v[210:211]
	v_pk_fma_f32 v[72:73], v[72:73], v[148:149], v[212:213]
	v_pk_fma_f32 v[74:75], v[74:75], v[150:151], v[214:215]
	v_pk_fma_f32 v[68:69], v[68:69], v[152:153], v[228:229]
	v_pk_fma_f32 v[70:71], v[70:71], v[154:155], v[230:231]
	global_load_dwordx4 v[204:207], v224, s[12:13]
	global_load_dwordx4 v[208:211], v224, s[12:13] offset:64
	global_load_dwordx4 v[212:215], v224, s[12:13] offset:512
	global_load_dwordx4 v[228:231], v224, s[12:13] offset:576
	v_mul_f32_e32 v132, v81, v81
	v_mul_f32_e32 v133, v83, v83
	v_fmac_f32_e32 v132, v80, v80
	v_fmac_f32_e32 v133, v82, v82
	v_add_f32_e32 v135, v132, v133
	v_mul_f32_e32 v132, v77, v77
	v_mul_f32_e32 v133, v79, v79
	v_fmac_f32_e32 v132, v76, v76
	v_fmac_f32_e32 v133, v78, v78
	v_add_f32_e32 v132, v132, v133
	v_add_f32_e32 v135, v135, v132
	v_mul_f32_e32 v132, v73, v73
	v_mul_f32_e32 v133, v75, v75
	v_fmac_f32_e32 v132, v72, v72
	v_fmac_f32_e32 v133, v74, v74
	v_add_f32_e32 v132, v132, v133
	v_add_f32_e32 v135, v135, v132
	v_mul_f32_e32 v132, v69, v69
	v_mul_f32_e32 v133, v71, v71
	v_fmac_f32_e32 v132, v68, v68
	v_fmac_f32_e32 v133, v70, v70
	v_add_f32_e32 v132, v132, v133
	v_add_f32_e32 v135, v135, v132
	ds_write_b32 v223, v135 offset:3072
	s_waitcnt vmcnt(12)
	v_pk_fma_f32 v[64:65], v[64:65], v[140:141], v[156:157]
	v_pk_fma_f32 v[66:67], v[66:67], v[142:143], v[158:159]
	v_pk_fma_f32 v[60:61], v[60:61], v[144:145], v[160:161]
	v_pk_fma_f32 v[62:63], v[62:63], v[146:147], v[162:163]
	v_pk_fma_f32 v[56:57], v[56:57], v[148:149], v[164:165]
	v_pk_fma_f32 v[58:59], v[58:59], v[150:151], v[166:167]
	v_pk_fma_f32 v[52:53], v[52:53], v[152:153], v[168:169]
	v_pk_fma_f32 v[54:55], v[54:55], v[154:155], v[170:171]
	v_mul_f32_e32 v132, v65, v65
	v_mul_f32_e32 v133, v67, v67
	v_fmac_f32_e32 v132, v64, v64
	v_fmac_f32_e32 v133, v66, v66
	v_add_f32_e32 v134, v132, v133
	v_mul_f32_e32 v132, v61, v61
	v_mul_f32_e32 v133, v63, v63
	v_fmac_f32_e32 v132, v60, v60
	v_fmac_f32_e32 v133, v62, v62
	v_add_f32_e32 v132, v132, v133
	v_add_f32_e32 v134, v134, v132
	v_mul_f32_e32 v132, v57, v57
	v_mul_f32_e32 v133, v59, v59
	v_fmac_f32_e32 v132, v56, v56
	v_fmac_f32_e32 v133, v58, v58
	v_add_f32_e32 v132, v132, v133
	v_add_f32_e32 v134, v134, v132
	v_mul_f32_e32 v132, v53, v53
	v_mul_f32_e32 v133, v55, v55
	v_fmac_f32_e32 v132, v52, v52
	v_fmac_f32_e32 v133, v54, v54
	v_add_f32_e32 v132, v132, v133
	v_add_f32_e32 v134, v134, v132
	ds_write_b32 v223, v134 offset:8192
	s_waitcnt vmcnt(8)
	v_pk_fma_f32 v[48:49], v[48:49], v[140:141], v[172:173]
	v_pk_fma_f32 v[50:51], v[50:51], v[142:143], v[174:175]
	v_pk_fma_f32 v[44:45], v[44:45], v[144:145], v[176:177]
	v_pk_fma_f32 v[46:47], v[46:47], v[146:147], v[178:179]
	v_pk_fma_f32 v[40:41], v[40:41], v[148:149], v[180:181]
	v_pk_fma_f32 v[42:43], v[42:43], v[150:151], v[182:183]
	v_pk_fma_f32 v[36:37], v[36:37], v[152:153], v[184:185]
	v_pk_fma_f32 v[38:39], v[38:39], v[154:155], v[186:187]
	v_mul_f32_e32 v132, v49, v49
	v_mul_f32_e32 v133, v51, v51
	v_fmac_f32_e32 v132, v48, v48
	v_fmac_f32_e32 v133, v50, v50
	v_add_f32_e32 v135, v132, v133
	v_mul_f32_e32 v132, v45, v45
	v_mul_f32_e32 v133, v47, v47
	v_fmac_f32_e32 v132, v44, v44
	v_fmac_f32_e32 v133, v46, v46
	v_add_f32_e32 v132, v132, v133
	v_add_f32_e32 v135, v135, v132
	v_mul_f32_e32 v132, v41, v41
	v_mul_f32_e32 v133, v43, v43
	v_fmac_f32_e32 v132, v40, v40
	v_fmac_f32_e32 v133, v42, v42
	v_add_f32_e32 v132, v132, v133
	v_add_f32_e32 v135, v135, v132
	v_mul_f32_e32 v132, v37, v37
	v_mul_f32_e32 v133, v39, v39
	v_fmac_f32_e32 v132, v36, v36
	v_fmac_f32_e32 v133, v38, v38
	v_add_f32_e32 v132, v132, v133
	v_add_f32_e32 v135, v135, v132
	ds_write_b32 v223, v135 offset:9216
	s_waitcnt vmcnt(4)
	v_pk_fma_f32 v[32:33], v[32:33], v[140:141], v[188:189]
	v_pk_fma_f32 v[34:35], v[34:35], v[142:143], v[190:191]
	v_pk_fma_f32 v[28:29], v[28:29], v[144:145], v[192:193]
	v_pk_fma_f32 v[30:31], v[30:31], v[146:147], v[194:195]
	v_pk_fma_f32 v[24:25], v[24:25], v[148:149], v[196:197]
	v_pk_fma_f32 v[26:27], v[26:27], v[150:151], v[198:199]
	v_pk_fma_f32 v[20:21], v[20:21], v[152:153], v[200:201]
	v_pk_fma_f32 v[22:23], v[22:23], v[154:155], v[202:203]
	v_mul_f32_e32 v132, v33, v33
	v_mul_f32_e32 v133, v35, v35
	v_fmac_f32_e32 v132, v32, v32
	v_fmac_f32_e32 v133, v34, v34
	v_add_f32_e32 v134, v132, v133
	v_mul_f32_e32 v132, v29, v29
	v_mul_f32_e32 v133, v31, v31
	v_fmac_f32_e32 v132, v28, v28
	v_fmac_f32_e32 v133, v30, v30
	v_add_f32_e32 v132, v132, v133
	v_add_f32_e32 v134, v134, v132
	v_mul_f32_e32 v132, v25, v25
	v_mul_f32_e32 v133, v27, v27
	v_fmac_f32_e32 v132, v24, v24
	v_fmac_f32_e32 v133, v26, v26
	v_add_f32_e32 v132, v132, v133
	v_add_f32_e32 v134, v134, v132
	v_mul_f32_e32 v132, v21, v21
	v_mul_f32_e32 v133, v23, v23
	v_fmac_f32_e32 v132, v20, v20
	v_fmac_f32_e32 v133, v22, v22
	v_add_f32_e32 v132, v132, v133
	v_add_f32_e32 v134, v134, v132
	ds_write_b32 v223, v134 offset:10240
	s_waitcnt vmcnt(0)
	v_pk_fma_f32 v[16:17], v[16:17], v[140:141], v[204:205]
	v_pk_fma_f32 v[18:19], v[18:19], v[142:143], v[206:207]
	v_pk_fma_f32 v[8:9], v[8:9], v[144:145], v[208:209]
	v_pk_fma_f32 v[10:11], v[10:11], v[146:147], v[210:211]
	v_pk_fma_f32 v[4:5], v[4:5], v[148:149], v[212:213]
	v_pk_fma_f32 v[6:7], v[6:7], v[150:151], v[214:215]
	v_pk_fma_f32 v[0:1], v[0:1], v[152:153], v[228:229]
	v_pk_fma_f32 v[2:3], v[2:3], v[154:155], v[230:231]
	v_mul_f32_e32 v132, v17, v17
	v_mul_f32_e32 v133, v19, v19
	v_fmac_f32_e32 v132, v16, v16
	v_fmac_f32_e32 v133, v18, v18
	v_add_f32_e32 v135, v132, v133
	v_mul_f32_e32 v132, v9, v9
	v_mul_f32_e32 v133, v11, v11
	v_fmac_f32_e32 v132, v8, v8
	v_fmac_f32_e32 v133, v10, v10
	v_add_f32_e32 v132, v132, v133
	v_add_f32_e32 v135, v135, v132
	v_mul_f32_e32 v132, v5, v5
	v_mul_f32_e32 v133, v7, v7
	v_fmac_f32_e32 v132, v4, v4
	v_fmac_f32_e32 v133, v6, v6
	v_add_f32_e32 v132, v132, v133
	v_add_f32_e32 v135, v135, v132
	v_mul_f32_e32 v132, v1, v1
	v_mul_f32_e32 v133, v3, v3
	v_fmac_f32_e32 v132, v0, v0
	v_fmac_f32_e32 v133, v2, v2
	v_add_f32_e32 v132, v132, v133
	v_add_f32_e32 v135, v135, v132
	ds_write_b32 v223, v135 offset:11264
	v_and_b32_e32 v15, 63, v216
	s_add_u32 s30, s30, 0x11200000
	s_addc_u32 s31, s31, 0
	s_waitcnt lgkmcnt(0)
	s_barrier
	s_and_b32 s0, s23, 0xffffffc0
	v_or_b32_e32 v12, s0, v15
	s_movk_i32 s0, 0x100
	v_cmp_gt_i32_e64 s[0:1], s0, v12
	s_waitcnt lgkmcnt(0)
	v_lshl_add_u32 v132, s22, 8, v12
	s_and_saveexec_b64 s[36:37], s[0:1]
	s_cbranch_execz .LBB0_381
	v_lshl_add_u32 v133, v12, 6, 0
	ds_read_b128 v[140:143], v133
	ds_read_b128 v[144:147], v133 offset:16
	ds_read_b128 v[148:151], v133 offset:32
	ds_read_b128 v[152:155], v133 offset:48
	v_ashrrev_i32_e32 v133, 31, v132
	s_ashr_i32 s21, s20, 31
	s_waitcnt lgkmcnt(0)
	v_add_f32_e32 v140, v140, v141
	v_add_f32_e32 v142, v142, v143
	v_add_f32_e32 v134, v140, v142
	v_add_f32_e32 v144, v144, v145
	v_add_f32_e32 v146, v146, v147
	v_add_f32_e32 v135, v144, v146
	v_add_f32_e32 v148, v148, v149
	v_add_f32_e32 v150, v150, v151
	v_add_f32_e32 v136, v148, v150
	v_add_f32_e32 v152, v152, v153
	v_add_f32_e32 v154, v154, v155
	v_add_f32_e32 v137, v152, v154
	v_mov_b32_e32 v138, v135
	v_mov_b32_e32 v139, v136
	v_mov_b32_e32 v135, v137
	v_pk_add_f32 v[134:135], v[138:139], v[134:135]
	v_lshlrev_b32_e32 v138, 1, v132
	v_mov_b32_e32 v139, 0
	v_lshl_add_u64 v[136:137], v[138:139], 4, s[30:31]
	v_pk_add_f32 v[134:135], v[134:135], v[134:135] op_sel:[0,1] op_sel_hi:[1,0]
	v_lshl_add_u64 v[136:137], s[20:21], 3, v[136:137]
	s_lshl_b32 s100, s80, 1
	s_add_u32 s100, s100, 0x13570000
	v_mov_b32_e32 v135, s100
	global_store_dwordx2 v[136:137], v[134:135], off sc1
.LBB0_381:
	s_or_b64 exec, exec, s[36:37]
	s_lshr_b32 s100, s22, 3
	s_mul_i32 s100, s100, 0x9000
	s_and_b64 vcc, exec, s[10:11]
	s_cselect_b32 s100, s100, 0
	s_cselect_b32 s101, 0x1000, 0
	v_add_u32_e32 v225, s101, v222
	s_add_u32 s100, s24, s100
	s_addc_u32 s101, s25, 0
	global_load_dwordx4 v[156:159], v222, s[100:101]
	global_load_dwordx4 v[160:163], v222, s[100:101] offset:64
	global_load_dwordx4 v[164:167], v222, s[100:101] offset:512
	global_load_dwordx4 v[168:171], v222, s[100:101] offset:576
	global_load_dwordx4 v[172:175], v225, s[100:101]
	global_load_dwordx4 v[176:179], v225, s[100:101] offset:64
	global_load_dwordx4 v[180:183], v225, s[100:101] offset:512
	global_load_dwordx4 v[184:187], v225, s[100:101] offset:576
.LBB0_394:
	s_and_saveexec_b64 s[28:29], s[0:1]
	s_cbranch_execz .LBB0_396
	v_lshlrev_b32_e32 v132, 1, v132
	v_mov_b32_e32 v133, 0
	v_lshl_add_u64 v[132:133], v[132:133], 4, s[30:31]
	s_lshl_b32 s100, s80, 1
	s_add_u32 s100, s100, 0x13570000
	s_mov_b32 s101, 0x8000
.Lxg_spin_0:
	global_load_dwordx4 v[140:143], v[132:133], off sc1
	global_load_dwordx4 v[144:147], v[132:133], off offset:16 sc1
	s_sub_u32 s101, s101, 1
	s_waitcnt vmcnt(0)
	v_cmp_ne_u32_e64 s[6:7], s100, v141
	v_cmp_ne_u32_e32 vcc, s100, v143
	s_nop 1
	s_or_b64 s[6:7], s[6:7], vcc
	v_cmp_ne_u32_e32 vcc, s100, v145
	s_nop 1
	s_or_b64 s[6:7], s[6:7], vcc
	v_cmp_ne_u32_e32 vcc, s100, v147
	s_nop 1
	s_or_b64 vcc, s[6:7], vcc
	s_cbranch_vccz .Lxg_ok_0
	s_sleep 2
	s_cmp_lg_u32 s101, 0
	s_cbranch_scc1 .Lxg_spin_0
.Lxg_ok_0:
	v_lshl_add_u32 v12, v12, 2, 0
	v_add_f32_e32 v15, 0, v140
	v_add_f32_e32 v15, v15, v142
	v_add_f32_e32 v15, v15, v144
	v_add_f32_e32 v15, v15, v146
	v_fmamk_f32 v15, v15, 0x3a800000, v218
	v_mul_f32_e32 v132, 0x4f800000, v15
	v_cmp_gt_f32_e32 vcc, s85, v15
	s_nop 1
	v_cndmask_b32_e32 v15, v15, v132, vcc
	v_sqrt_f32_e32 v132, v15
	s_nop 0
	v_add_u32_e32 v133, -1, v132
	v_add_u32_e32 v134, 1, v132
	v_fma_f32 v135, -v133, v132, v15
	v_fma_f32 v136, -v134, v132, v15
	v_cmp_ge_f32_e64 s[0:1], 0, v135
	s_nop 1
	v_cndmask_b32_e64 v132, v132, v133, s[0:1]
	v_cmp_lt_f32_e64 s[0:1], 0, v136
	s_nop 1
	v_cndmask_b32_e64 v132, v132, v134, s[0:1]
	v_mul_f32_e32 v133, 0x37800000, v132
	v_cndmask_b32_e32 v132, v132, v133, vcc
	v_cmp_class_f32_e32 vcc, v15, v219
	s_nop 1
	v_cndmask_b32_e32 v15, v132, v15, vcc
	v_div_scale_f32 v132, s[0:1], v15, v15, 1.0
	v_rcp_f32_e32 v133, v132
	v_div_scale_f32 v134, vcc, 1.0, v15, 1.0
	v_fma_f32 v135, -v132, v133, 1.0
	v_fmac_f32_e32 v133, v135, v133
	v_mul_f32_e32 v135, v134, v133
	v_fma_f32 v136, -v132, v135, v134
	v_fmac_f32_e32 v135, v136, v133
	v_fma_f32 v132, -v132, v135, v134
	v_div_fmas_f32 v132, v132, v133, v135
	v_div_fixup_f32 v15, v132, v15, 1.0
	ds_write_b32 v12, v15 offset:16384

.LBB0_935:
	v_mov_b32_e32 v12, v216
	s_cmpk_lg_i32 s70, 0x100
	s_waitcnt vmcnt(0)
	s_barrier
	s_cselect_b64 s[22:23], -1, 0
	v_readfirstlane_b32 s7, v12
	s_ashr_i32 s28, s7, 8
	s_bfe_u32 s29, s7, 0x20006
	s_cmp_eq_u32 s89, 16
	s_cselect_b64 s[20:21], -1, 0
	s_cmp_lg_u32 s89, 16
	s_cselect_b64 s[24:25], -1, 0
	s_or_b64 s[22:23], s[22:23], s[24:25]
	s_cmp_gt_i32 s10, 63
	s_cselect_b64 s[24:25], -1, 0
	v_readlane_b32 s78, v254, 8
	s_or_b64 s[22:23], s[22:23], s[24:25]
	v_readlane_b32 s76, v254, 6
	v_readlane_b32 s79, v254, 9
	v_readlane_b32 s80, v254, 21
	v_and_b32_e32 v182, 15, v12
	v_bfe_u32 v183, v12, 4, 2
	s_andn2_b64 vcc, exec, s[22:23]
	s_mov_b64 s[22:23], -1
	v_readlane_b32 s77, v254, 7
	v_readlane_b32 s75, v254, 10
	v_readlane_b32 s81, v254, 22
	s_movk_i32 s79, 0x5000
	s_mov_b32 s82, 0x1400000
	s_mov_b32 s83, 0x1800000
	s_mov_b32 s84, 0x1c00000
	s_mov_b32 s85, 0xf800000
	s_movk_i32 s86, 0x1000
	s_movk_i32 s87, 0x48
	s_movk_i32 s88, 0x1600
	s_cbranch_vccz .LBB0_970
	s_waitcnt vmcnt(0)
	v_lshl_or_b32 v14, s28, 6, v182
	s_lshl_b32 s100, s8, 8
	s_lshl_b32 s101, s29, 5
	s_or_b32 s100, s100, s101
	v_lshl_or_b32 v225, v183, 2, s100
	v_lshlrev_b32_e32 v222, 2, v225
	s_lshl_b32 s100, s10, 8
	v_add_u32_e32 v12, s100, v14
	v_lshl_add_u32 v12, v12, 10, v225
	v_lshlrev_b32_e32 v220, 2, v12
	v_mov_b32_e32 v224, v220
	v_lshlrev_b32_e32 v221, 2, v14
	s_lshl_b32 s100, s29, 4
	v_lshl_add_u32 v223, v14, 6, s100
	v_lshl_add_u32 v223, v183, 2, v223
	s_lshr_b32 s100, s10, 3
	s_mul_i32 s100, s100, 0x9000
	s_add_u32 s100, s47, s100
	s_addc_u32 s101, s62, 0
	global_load_dwordx4 v[140:143], v222, s[100:101]
	global_load_dwordx4 v[144:147], v222, s[100:101] offset:64
	global_load_dwordx4 v[148:151], v222, s[100:101] offset:512
	global_load_dwordx4 v[152:155], v222, s[100:101] offset:576
	global_load_dwordx4 v[156:159], v224, s[2:3]
	global_load_dwordx4 v[160:163], v224, s[2:3] offset:64
	global_load_dwordx4 v[164:167], v224, s[2:3] offset:512
	global_load_dwordx4 v[168:171], v224, s[2:3] offset:576
	v_add_u32_e32 v224, 0x10000, v224
	global_load_dwordx4 v[172:175], v224, s[2:3]
	global_load_dwordx4 v[176:179], v224, s[2:3] offset:64
	global_load_dwordx4 v[180:183], v224, s[2:3] offset:512
	global_load_dwordx4 v[184:187], v224, s[2:3] offset:576
	v_add_u32_e32 v224, 0x10000, v224
	global_load_dwordx4 v[188:191], v224, s[2:3]
	global_load_dwordx4 v[192:195], v224, s[2:3] offset:64
	global_load_dwordx4 v[196:199], v224, s[2:3] offset:512
	global_load_dwordx4 v[200:203], v224, s[2:3] offset:576
	v_add_u32_e32 v224, 0x10000, v224
	global_load_dwordx4 v[204:207], v224, s[2:3]
	global_load_dwordx4 v[208:211], v224, s[2:3] offset:64
	global_load_dwordx4 v[212:215], v224, s[2:3] offset:512
	global_load_dwordx4 v[228:231], v224, s[2:3] offset:576
	v_add_u32_e32 v224, 0x50000, v224
	s_waitcnt vmcnt(12)
	v_pk_fma_f32 v[128:129], v[128:129], v[140:141], v[156:157]
	v_pk_fma_f32 v[130:131], v[130:131], v[142:143], v[158:159]
	v_pk_fma_f32 v[124:125], v[124:125], v[144:145], v[160:161]
	v_pk_fma_f32 v[126:127], v[126:127], v[146:147], v[162:163]
	v_pk_fma_f32 v[120:121], v[120:121], v[148:149], v[164:165]
	v_pk_fma_f32 v[122:123], v[122:123], v[150:151], v[166:167]
	v_pk_fma_f32 v[116:117], v[116:117], v[152:153], v[168:169]
	v_pk_fma_f32 v[118:119], v[118:119], v[154:155], v[170:171]
	global_load_dwordx4 v[156:159], v224, s[2:3]
	global_load_dwordx4 v[160:163], v224, s[2:3] offset:64
	global_load_dwordx4 v[164:167], v224, s[2:3] offset:512
	global_load_dwordx4 v[168:171], v224, s[2:3] offset:576
	v_add_u32_e32 v224, 0x10000, v224
	v_mul_f32_e32 v132, v129, v129
	v_mul_f32_e32 v133, v131, v131
	v_fmac_f32_e32 v132, v128, v128
	v_fmac_f32_e32 v133, v130, v130
	v_add_f32_e32 v134, v132, v133
	v_mul_f32_e32 v132, v125, v125
	v_mul_f32_e32 v133, v127, v127
	v_fmac_f32_e32 v132, v124, v124
	v_fmac_f32_e32 v133, v126, v126
	v_add_f32_e32 v132, v132, v133
	v_add_f32_e32 v134, v134, v132
	v_mul_f32_e32 v132, v121, v121
	v_mul_f32_e32 v133, v123, v123
	v_fmac_f32_e32 v132, v120, v120
	v_fmac_f32_e32 v133, v122, v122
	v_add_f32_e32 v132, v132, v133
	v_add_f32_e32 v134, v134, v132
	v_mul_f32_e32 v132, v117, v117
	v_mul_f32_e32 v133, v119, v119
	v_fmac_f32_e32 v132, v116, v116
	v_fmac_f32_e32 v133, v118, v118
	v_add_f32_e32 v132, v132, v133
	v_add_f32_e32 v134, v134, v132
	ds_write_b32 v223, v134
	s_waitcnt vmcnt(12)
	v_pk_fma_f32 v[112:113], v[112:113], v[140:141], v[172:173]
	v_pk_fma_f32 v[114:115], v[114:115], v[142:143], v[174:175]
	v_pk_fma_f32 v[108:109], v[108:109], v[144:145], v[176:177]
	v_pk_fma_f32 v[110:111], v[110:111], v[146:147], v[178:179]
	v_pk_fma_f32 v[104:105], v[104:105], v[148:149], v[180:181]
	v_pk_fma_f32 v[106:107], v[106:107], v[150:151], v[182:183]
	v_pk_fma_f32 v[100:101], v[100:101], v[152:153], v[184:185]
	v_pk_fma_f32 v[102:103], v[102:103], v[154:155], v[186:187]
	global_load_dwordx4 v[172:175], v224, s[2:3]
	global_load_dwordx4 v[176:179], v224, s[2:3] offset:64
	global_load_dwordx4 v[180:183], v224, s[2:3] offset:512
	global_load_dwordx4 v[184:187], v224, s[2:3] offset:576
	v_add_u32_e32 v224, 0x10000, v224
	v_mul_f32_e32 v132, v113, v113
	v_mul_f32_e32 v133, v115, v115
	v_fmac_f32_e32 v132, v112, v112
	v_fmac_f32_e32 v133, v114, v114
	v_add_f32_e32 v135, v132, v133
	v_mul_f32_e32 v132, v109, v109
	v_mul_f32_e32 v133, v111, v111
	v_fmac_f32_e32 v132, v108, v108
	v_fmac_f32_e32 v133, v110, v110
	v_add_f32_e32 v132, v132, v133
	v_add_f32_e32 v135, v135, v132
	v_mul_f32_e32 v132, v105, v105
	v_mul_f32_e32 v133, v107, v107
	v_fmac_f32_e32 v132, v104, v104
	v_fmac_f32_e32 v133, v106, v106
	v_add_f32_e32 v132, v132, v133
	v_add_f32_e32 v135, v135, v132
	v_mul_f32_e32 v132, v101, v101
	v_mul_f32_e32 v133, v103, v103
	v_fmac_f32_e32 v132, v100, v100
	v_fmac_f32_e32 v133, v102, v102
	v_add_f32_e32 v132, v132, v133
	v_add_f32_e32 v135, v135, v132
	ds_write_b32 v223, v135 offset:1024
	s_waitcnt vmcnt(12)
	v_pk_fma_f32 v[96:97], v[96:97], v[140:141], v[188:189]
	v_pk_fma_f32 v[98:99], v[98:99], v[142:143], v[190:191]
	v_pk_fma_f32 v[92:93], v[92:93], v[144:145], v[192:193]
	v_pk_fma_f32 v[94:95], v[94:95], v[146:147], v[194:195]
	v_pk_fma_f32 v[88:89], v[88:89], v[148:149], v[196:197]
	v_pk_fma_f32 v[90:91], v[90:91], v[150:151], v[198:199]
	v_pk_fma_f32 v[84:85], v[84:85], v[152:153], v[200:201]
	v_pk_fma_f32 v[86:87], v[86:87], v[154:155], v[202:203]
	global_load_dwordx4 v[188:191], v224, s[2:3]
	global_load_dwordx4 v[192:195], v224, s[2:3] offset:64
	global_load_dwordx4 v[196:199], v224, s[2:3] offset:512
	global_load_dwordx4 v[200:203], v224, s[2:3] offset:576
	v_add_u32_e32 v224, 0x10000, v224
	v_mul_f32_e32 v132, v97, v97
	v_mul_f32_e32 v133, v99, v99
	v_fmac_f32_e32 v132, v96, v96
	v_fmac_f32_e32 v133, v98, v98
	v_add_f32_e32 v134, v132, v133
	v_mul_f32_e32 v132, v93, v93
	v_mul_f32_e32 v133, v95, v95
	v_fmac_f32_e32 v132, v92, v92
	v_fmac_f32_e32 v133, v94, v94
	v_add_f32_e32 v132, v132, v133
	v_add_f32_e32 v134, v134, v132
	v_mul_f32_e32 v132, v89, v89
	v_mul_f32_e32 v133, v91, v91
	v_fmac_f32_e32 v132, v88, v88
	v_fmac_f32_e32 v133, v90, v90
	v_add_f32_e32 v132, v132, v133
	v_add_f32_e32 v134, v134, v132
	v_mul_f32_e32 v132, v85, v85
	v_mul_f32_e32 v133, v87, v87
	v_fmac_f32_e32 v132, v84, v84
	v_fmac_f32_e32 v133, v86, v86
	v_add_f32_e32 v132, v132, v133
	v_add_f32_e32 v134, v134, v132
	ds_write_b32 v223, v134 offset:2048
	s_waitcnt vmcnt(12)
	v_pk_fma_f32 v[80:81], v[80:81], v[140:141], v[204:205]
	v_pk_fma_f32 v[82:83], v[82:83], v[142:143], v[206:207]
	v_pk_fma_f32 v[76:77], v[76:77], v[144:145], v[208:209]
	v_pk_fma_f32 v[78:79], v[78:79], v[146:147], v[210:211]
	v_pk_fma_f32 v[72:73], v[72:73], v[148:149], v[212:213]
	v_pk_fma_f32 v[74:75], v[74:75], v[150:151], v[214:215]
	v_pk_fma_f32 v[68:69], v[68:69], v[152:153], v[228:229]
	v_pk_fma_f32 v[70:71], v[70:71], v[154:155], v[230:231]
	global_load_dwordx4 v[204:207], v224, s[2:3]
	global_load_dwordx4 v[208:211], v224, s[2:3] offset:64
	global_load_dwordx4 v[212:215], v224, s[2:3] offset:512
	global_load_dwordx4 v[228:231], v224, s[2:3] offset:576
	v_mul_f32_e32 v132, v81, v81
	v_mul_f32_e32 v133, v83, v83
	v_fmac_f32_e32 v132, v80, v80
	v_fmac_f32_e32 v133, v82, v82
	v_add_f32_e32 v135, v132, v133
	v_mul_f32_e32 v132, v77, v77
	v_mul_f32_e32 v133, v79, v79
	v_fmac_f32_e32 v132, v76, v76
	v_fmac_f32_e32 v133, v78, v78
	v_add_f32_e32 v132, v132, v133
	v_add_f32_e32 v135, v135, v132
	v_mul_f32_e32 v132, v73, v73
	v_mul_f32_e32 v133, v75, v75
	v_fmac_f32_e32 v132, v72, v72
	v_fmac_f32_e32 v133, v74, v74
	v_add_f32_e32 v132, v132, v133
	v_add_f32_e32 v135, v135, v132
	v_mul_f32_e32 v132, v69, v69
	v_mul_f32_e32 v133, v71, v71
	v_fmac_f32_e32 v132, v68, v68
	v_fmac_f32_e32 v133, v70, v70
	v_add_f32_e32 v132, v132, v133
	v_add_f32_e32 v135, v135, v132
	ds_write_b32 v223, v135 offset:3072
	s_waitcnt vmcnt(12)
	v_pk_fma_f32 v[64:65], v[64:65], v[140:141], v[156:157]
	v_pk_fma_f32 v[66:67], v[66:67], v[142:143], v[158:159]
	v_pk_fma_f32 v[60:61], v[60:61], v[144:145], v[160:161]
	v_pk_fma_f32 v[62:63], v[62:63], v[146:147], v[162:163]
	v_pk_fma_f32 v[56:57], v[56:57], v[148:149], v[164:165]
	v_pk_fma_f32 v[58:59], v[58:59], v[150:151], v[166:167]
	v_pk_fma_f32 v[52:53], v[52:53], v[152:153], v[168:169]
	v_pk_fma_f32 v[54:55], v[54:55], v[154:155], v[170:171]
	v_mul_f32_e32 v132, v65, v65
	v_mul_f32_e32 v133, v67, v67
	v_fmac_f32_e32 v132, v64, v64
	v_fmac_f32_e32 v133, v66, v66
	v_add_f32_e32 v134, v132, v133
	v_mul_f32_e32 v132, v61, v61
	v_mul_f32_e32 v133, v63, v63
	v_fmac_f32_e32 v132, v60, v60
	v_fmac_f32_e32 v133, v62, v62
	v_add_f32_e32 v132, v132, v133
	v_add_f32_e32 v134, v134, v132
	v_mul_f32_e32 v132, v57, v57
	v_mul_f32_e32 v133, v59, v59
	v_fmac_f32_e32 v132, v56, v56
	v_fmac_f32_e32 v133, v58, v58
	v_add_f32_e32 v132, v132, v133
	v_add_f32_e32 v134, v134, v132
	v_mul_f32_e32 v132, v53, v53
	v_mul_f32_e32 v133, v55, v55
	v_fmac_f32_e32 v132, v52, v52
	v_fmac_f32_e32 v133, v54, v54
	v_add_f32_e32 v132, v132, v133
	v_add_f32_e32 v134, v134, v132
	ds_write_b32 v223, v134 offset:8192
	s_waitcnt vmcnt(8)
	v_pk_fma_f32 v[48:49], v[48:49], v[140:141], v[172:173]
	v_pk_fma_f32 v[50:51], v[50:51], v[142:143], v[174:175]
	v_pk_fma_f32 v[44:45], v[44:45], v[144:145], v[176:177]
	v_pk_fma_f32 v[46:47], v[46:47], v[146:147], v[178:179]
	v_pk_fma_f32 v[40:41], v[40:41], v[148:149], v[180:181]
	v_pk_fma_f32 v[42:43], v[42:43], v[150:151], v[182:183]
	v_pk_fma_f32 v[36:37], v[36:37], v[152:153], v[184:185]
	v_pk_fma_f32 v[38:39], v[38:39], v[154:155], v[186:187]
	v_mul_f32_e32 v132, v49, v49
	v_mul_f32_e32 v133, v51, v51
	v_fmac_f32_e32 v132, v48, v48
	v_fmac_f32_e32 v133, v50, v50
	v_add_f32_e32 v135, v132, v133
	v_mul_f32_e32 v132, v45, v45
	v_mul_f32_e32 v133, v47, v47
	v_fmac_f32_e32 v132, v44, v44
	v_fmac_f32_e32 v133, v46, v46
	v_add_f32_e32 v132, v132, v133
	v_add_f32_e32 v135, v135, v132
	v_mul_f32_e32 v132, v41, v41
	v_mul_f32_e32 v133, v43, v43
	v_fmac_f32_e32 v132, v40, v40
	v_fmac_f32_e32 v133, v42, v42
	v_add_f32_e32 v132, v132, v133
	v_add_f32_e32 v135, v135, v132
	v_mul_f32_e32 v132, v37, v37
	v_mul_f32_e32 v133, v39, v39
	v_fmac_f32_e32 v132, v36, v36
	v_fmac_f32_e32 v133, v38, v38
	v_add_f32_e32 v132, v132, v133
	v_add_f32_e32 v135, v135, v132
	ds_write_b32 v223, v135 offset:9216
	s_waitcnt vmcnt(4)
	v_pk_fma_f32 v[32:33], v[32:33], v[140:141], v[188:189]
	v_pk_fma_f32 v[34:35], v[34:35], v[142:143], v[190:191]
	v_pk_fma_f32 v[28:29], v[28:29], v[144:145], v[192:193]
	v_pk_fma_f32 v[30:31], v[30:31], v[146:147], v[194:195]
	v_pk_fma_f32 v[24:25], v[24:25], v[148:149], v[196:197]
	v_pk_fma_f32 v[26:27], v[26:27], v[150:151], v[198:199]
	v_pk_fma_f32 v[20:21], v[20:21], v[152:153], v[200:201]
	v_pk_fma_f32 v[22:23], v[22:23], v[154:155], v[202:203]
	v_mul_f32_e32 v132, v33, v33
	v_mul_f32_e32 v133, v35, v35
	v_fmac_f32_e32 v132, v32, v32
	v_fmac_f32_e32 v133, v34, v34
	v_add_f32_e32 v134, v132, v133
	v_mul_f32_e32 v132, v29, v29
	v_mul_f32_e32 v133, v31, v31
	v_fmac_f32_e32 v132, v28, v28
	v_fmac_f32_e32 v133, v30, v30
	v_add_f32_e32 v132, v132, v133
	v_add_f32_e32 v134, v134, v132
	v_mul_f32_e32 v132, v25, v25
	v_mul_f32_e32 v133, v27, v27
	v_fmac_f32_e32 v132, v24, v24
	v_fmac_f32_e32 v133, v26, v26
	v_add_f32_e32 v132, v132, v133
	v_add_f32_e32 v134, v134, v132
	v_mul_f32_e32 v132, v21, v21
	v_mul_f32_e32 v133, v23, v23
	v_fmac_f32_e32 v132, v20, v20
	v_fmac_f32_e32 v133, v22, v22
	v_add_f32_e32 v132, v132, v133
	v_add_f32_e32 v134, v134, v132
	ds_write_b32 v223, v134 offset:10240
	s_waitcnt vmcnt(0)
	v_pk_fma_f32 v[16:17], v[16:17], v[140:141], v[204:205]
	v_pk_fma_f32 v[18:19], v[18:19], v[142:143], v[206:207]
	v_pk_fma_f32 v[8:9], v[8:9], v[144:145], v[208:209]
	v_pk_fma_f32 v[10:11], v[10:11], v[146:147], v[210:211]
	v_pk_fma_f32 v[4:5], v[4:5], v[148:149], v[212:213]
	v_pk_fma_f32 v[6:7], v[6:7], v[150:151], v[214:215]
	v_pk_fma_f32 v[0:1], v[0:1], v[152:153], v[228:229]
	v_pk_fma_f32 v[2:3], v[2:3], v[154:155], v[230:231]
	v_mul_f32_e32 v132, v17, v17
	v_mul_f32_e32 v133, v19, v19
	v_fmac_f32_e32 v132, v16, v16
	v_fmac_f32_e32 v133, v18, v18
	v_add_f32_e32 v135, v132, v133
	v_mul_f32_e32 v132, v9, v9
	v_mul_f32_e32 v133, v11, v11
	v_fmac_f32_e32 v132, v8, v8
	v_fmac_f32_e32 v133, v10, v10
	v_add_f32_e32 v132, v132, v133
	v_add_f32_e32 v135, v135, v132
	v_mul_f32_e32 v132, v5, v5
	v_mul_f32_e32 v133, v7, v7
	v_fmac_f32_e32 v132, v4, v4
	v_fmac_f32_e32 v133, v6, v6
	v_add_f32_e32 v132, v132, v133
	v_add_f32_e32 v135, v135, v132
	v_mul_f32_e32 v132, v1, v1
	v_mul_f32_e32 v133, v3, v3
	v_fmac_f32_e32 v132, v0, v0
	v_fmac_f32_e32 v133, v2, v2
	v_add_f32_e32 v132, v132, v133
	v_add_f32_e32 v135, v135, v132
	ds_write_b32 v223, v135 offset:11264
	v_and_b32_e32 v15, 63, v216
	s_add_u32 s24, s0, 0x11200000
	s_addc_u32 s25, s1, 0
	s_waitcnt lgkmcnt(0)
	s_barrier
	s_and_b32 s0, s7, 0xffffffc0
	v_or_b32_e32 v12, s0, v15
	s_movk_i32 s0, 0x100
	v_cmp_gt_i32_e64 s[0:1], s0, v12
	s_waitcnt lgkmcnt(0)
	v_lshl_add_u32 v132, s10, 8, v12
	s_and_saveexec_b64 s[26:27], s[0:1]
	s_cbranch_execz .LBB0_954
	v_lshl_add_u32 v133, v12, 6, 0
	ds_read_b128 v[140:143], v133
	ds_read_b128 v[144:147], v133 offset:16
	ds_read_b128 v[148:151], v133 offset:32
	ds_read_b128 v[152:155], v133 offset:48
	v_ashrrev_i32_e32 v133, 31, v132
	s_ashr_i32 s9, s8, 31
	s_waitcnt lgkmcnt(0)
	v_add_f32_e32 v140, v140, v141
	v_add_f32_e32 v142, v142, v143
	v_add_f32_e32 v134, v140, v142
	v_add_f32_e32 v144, v144, v145
	v_add_f32_e32 v146, v146, v147
	v_add_f32_e32 v135, v144, v146
	v_add_f32_e32 v148, v148, v149
	v_add_f32_e32 v150, v150, v151
	v_add_f32_e32 v136, v148, v150
	v_add_f32_e32 v152, v152, v153
	v_add_f32_e32 v154, v154, v155
	v_add_f32_e32 v137, v152, v154
	v_mov_b32_e32 v138, v135
	v_mov_b32_e32 v139, v136
	v_mov_b32_e32 v135, v137
	v_pk_add_f32 v[134:135], v[138:139], v[134:135]
	v_lshlrev_b32_e32 v138, 1, v132
	v_mov_b32_e32 v139, 0
	v_lshl_add_u64 v[136:137], v[138:139], 4, s[24:25]
	v_pk_add_f32 v[134:135], v[134:135], v[134:135] op_sel:[0,1] op_sel_hi:[1,0]
	v_lshl_add_u64 v[136:137], s[8:9], 3, v[136:137]
	v_readlane_b32 s100, v254, 11
	s_lshl_b32 s100, s100, 1
	s_add_u32 s100, s100, 0x13570001
	v_mov_b32_e32 v135, s100
	global_store_dwordx2 v[136:137], v[134:135], off sc1
.LBB0_954:
	s_or_b64 exec, exec, s[26:27]
	s_lshr_b32 s100, s10, 3
	s_mul_i32 s100, s100, 0x9000
	v_add_u32_e32 v225, 0x1000, v222
	s_add_u32 s100, s100, 0x46000
	s_add_u32 s100, s14, s100
	s_addc_u32 s101, s15, 0
	s_add_u32 s100, s18, s100
	s_addc_u32 s101, s19, s101
	global_load_dwordx4 v[156:159], v222, s[100:101]
	global_load_dwordx4 v[160:163], v222, s[100:101] offset:64
	global_load_dwordx4 v[164:167], v222, s[100:101] offset:512
	global_load_dwordx4 v[168:171], v222, s[100:101] offset:576
	global_load_dwordx4 v[172:175], v225, s[100:101]
	global_load_dwordx4 v[176:179], v225, s[100:101] offset:64
	global_load_dwordx4 v[180:183], v225, s[100:101] offset:512
	global_load_dwordx4 v[184:187], v225, s[100:101] offset:576
.LBB0_967:
	s_and_saveexec_b64 s[16:17], s[0:1]
	s_cbranch_execz .LBB0_969
	v_lshlrev_b32_e32 v132, 1, v132
	v_mov_b32_e32 v133, 0
	v_lshl_add_u64 v[132:133], v[132:133], 4, s[24:25]
	v_readlane_b32 s100, v254, 11
	s_lshl_b32 s100, s100, 1
	s_add_u32 s100, s100, 0x13570001
	s_mov_b32 s101, 0x8000
.Lxg_spin_1:
	global_load_dwordx4 v[140:143], v[132:133], off sc1
	global_load_dwordx4 v[144:147], v[132:133], off offset:16 sc1
	s_sub_u32 s101, s101, 1
	s_waitcnt vmcnt(0)
	v_cmp_ne_u32_e64 s[30:31], s100, v141
	v_cmp_ne_u32_e32 vcc, s100, v143
	s_nop 1
	s_or_b64 s[30:31], s[30:31], vcc
	v_cmp_ne_u32_e32 vcc, s100, v145
	s_nop 1
	s_or_b64 s[30:31], s[30:31], vcc
	v_cmp_ne_u32_e32 vcc, s100, v147
	s_nop 1
	s_or_b64 vcc, s[30:31], vcc
	s_cbranch_vccz .Lxg_ok_1
	s_sleep 2
	s_cmp_lg_u32 s101, 0
	s_cbranch_scc1 .Lxg_spin_1
